# waves 4-7 at static priority 1 for the whole layer loop (one raise at the loop head, no resets), GEMM per-block toggles removed
# baseline (speedup 1.0000x reference)
.LBB0_358:
	v_readfirstlane_b32 s100, v244
	s_nop 0
	s_lshr_b32 s100, s100, 6
	s_cmp_lt_u32 s100, 4
	s_cbranch_scc1 .Lprio_L
	s_setprio 1
